# grid barrier: XCD leader bumps the per-XCD generation before issuing its own L1 invalidate (10 of 11 sites)
# speedup vs baseline: 1.0022x; 1.0022x over previous
; __device__ __forceinline__ unsigned xb_add(unsigned* p, unsigned v) { return __hip_atomic_fetch_add(p, v, __ATOMIC_RELAXED, __HIP_MEMORY_SCOPE_AGENT); }
; __device__ __forceinline__ void xcd_barrier(const XcdBarrier& b, const bool leader) {
;     ...
;             __builtin_amdgcn_fence(__ATOMIC_ACQUIRE, "agent");
;             xb_add(&bar[XB_XGEN(b.x)], 1u);
;             asm volatile("s_waitcnt vmcnt(0)" ::: "memory");
.LBB0_80:
	s_or_b64 exec, exec, s[8:9]
	s_mov_b64 s[8:9], exec
	v_mbcnt_lo_u32_b32 v2, s8, 0
	v_mbcnt_hi_u32_b32 v2, s9, v2
	v_cmp_eq_u32_e32 vcc, 0, v2
	s_waitcnt vmcnt(0)
	s_and_saveexec_b64 s[10:11], vcc
	s_cbranch_execz .LBB0_82
	s_bcnt1_i32_b64 s1, s[8:9]
	v_mov_b32_e32 v2, 0x2000
	v_mov_b32_e32 v3, s1
	global_atomic_add v2, v3, s[6:7] offset:1024
.LBB0_82:
	s_or_b64 exec, exec, s[10:11]
	buffer_inv sc1
	s_waitcnt vmcnt(0)

; __device__ __forceinline__ unsigned xb_add(unsigned* p, unsigned v) { return __hip_atomic_fetch_add(p, v, __ATOMIC_RELAXED, __HIP_MEMORY_SCOPE_AGENT); }
; __device__ __forceinline__ void xcd_barrier(const XcdBarrier& b, const bool leader) {
;     ...
;             __builtin_amdgcn_fence(__ATOMIC_ACQUIRE, "agent");
;             xb_add(&bar[XB_XGEN(b.x)], 1u);
.LBB0_341:
	s_or_b64 exec, exec, s[4:5]
	s_mov_b64 s[4:5], exec
	v_mbcnt_lo_u32_b32 v2, s4, 0
	v_mbcnt_hi_u32_b32 v2, s5, v2
	v_cmp_eq_u32_e32 vcc, 0, v2
	s_waitcnt vmcnt(0)
	s_and_saveexec_b64 s[10:11], vcc
	s_cbranch_execz .LBB0_343
	s_bcnt1_i32_b64 s1, s[4:5]
	v_mov_b32_e32 v2, 0x2000
	v_mov_b32_e32 v3, s1
	global_atomic_add v2, v3, s[8:9] offset:1024

; __device__ __forceinline__ unsigned xb_add(unsigned* p, unsigned v) { return __hip_atomic_fetch_add(p, v, __ATOMIC_RELAXED, __HIP_MEMORY_SCOPE_AGENT); }
; __device__ __forceinline__ void xcd_barrier(const XcdBarrier& b, const bool leader) {
;     ...
;             __builtin_amdgcn_fence(__ATOMIC_ACQUIRE, "agent");
;             xb_add(&bar[XB_XGEN(b.x)], 1u);
;             asm volatile("s_waitcnt vmcnt(0)" ::: "memory");
.LBB0_501:
	s_or_b64 exec, exec, s[6:7]
	s_mov_b64 s[14:15], exec
	v_mbcnt_lo_u32_b32 v2, s14, 0
	v_mbcnt_hi_u32_b32 v2, s15, v2
	v_cmp_eq_u32_e32 vcc, 0, v2
	s_waitcnt vmcnt(0)
	s_and_saveexec_b64 s[6:7], vcc
	s_cbranch_execz .LBB0_503
	s_bcnt1_i32_b64 s2, s[14:15]
	v_mov_b32_e32 v2, s2
	global_atomic_add v202, v2, s[10:11] offset:1024
.LBB0_503:
	s_or_b64 exec, exec, s[6:7]
	buffer_inv sc1
	s_waitcnt vmcnt(0)

; __device__ __forceinline__ unsigned xb_add(unsigned* p, unsigned v) { return __hip_atomic_fetch_add(p, v, __ATOMIC_RELAXED, __HIP_MEMORY_SCOPE_AGENT); }
; __device__ __forceinline__ void xcd_barrier(const XcdBarrier& b, const bool leader) {
;     ...
;             __builtin_amdgcn_fence(__ATOMIC_ACQUIRE, "agent");
;             xb_add(&bar[XB_XGEN(b.x)], 1u);
.LBB0_613:
	s_or_b64 exec, exec, s[6:7]
	s_mov_b64 s[10:11], exec
	v_mbcnt_lo_u32_b32 v2, s10, 0
	v_mbcnt_hi_u32_b32 v2, s11, v2
	v_cmp_eq_u32_e32 vcc, 0, v2
	s_waitcnt vmcnt(0)
	s_and_saveexec_b64 s[6:7], vcc
	s_cbranch_execz .LBB0_615
	s_bcnt1_i32_b64 s2, s[10:11]
	v_mov_b32_e32 v2, s2
	global_atomic_add v202, v2, s[8:9] offset:1024

; __device__ __forceinline__ unsigned xb_add(unsigned* p, unsigned v) { return __hip_atomic_fetch_add(p, v, __ATOMIC_RELAXED, __HIP_MEMORY_SCOPE_AGENT); }
; __device__ __forceinline__ void xcd_barrier(const XcdBarrier& b, const bool leader) {
;     ...
;             __builtin_amdgcn_fence(__ATOMIC_ACQUIRE, "agent");
;             xb_add(&bar[XB_XGEN(b.x)], 1u);
.LBB0_691:
	s_or_b64 exec, exec, s[4:5]
	s_mov_b64 s[4:5], exec
	v_mbcnt_lo_u32_b32 v2, s4, 0
	v_mbcnt_hi_u32_b32 v2, s5, v2
	v_cmp_eq_u32_e32 vcc, 0, v2
	s_waitcnt vmcnt(0)
	s_and_saveexec_b64 s[6:7], vcc
	s_cbranch_execz .LBB0_693
	s_bcnt1_i32_b64 s2, s[4:5]
	v_mov_b32_e32 v2, s2
	global_atomic_add v202, v2, s[10:11] offset:1024

; __device__ __forceinline__ unsigned xb_add(unsigned* p, unsigned v) { return __hip_atomic_fetch_add(p, v, __ATOMIC_RELAXED, __HIP_MEMORY_SCOPE_AGENT); }
; __device__ __forceinline__ void xcd_barrier(const XcdBarrier& b, const bool leader) {
;     ...
;             __builtin_amdgcn_fence(__ATOMIC_ACQUIRE, "agent");
;             xb_add(&bar[XB_XGEN(b.x)], 1u);
.LBB0_852:
	s_or_b64 exec, exec, s[6:7]
	s_mov_b64 s[12:13], exec
	v_mbcnt_lo_u32_b32 v2, s12, 0
	v_mbcnt_hi_u32_b32 v2, s13, v2
	v_cmp_eq_u32_e32 vcc, 0, v2
	s_waitcnt vmcnt(0)
	s_and_saveexec_b64 s[6:7], vcc
	s_cbranch_execz .LBB0_854
	s_bcnt1_i32_b64 s2, s[12:13]
	v_mov_b32_e32 v2, s2
	global_atomic_add v202, v2, s[14:15] offset:1024

; __device__ __forceinline__ unsigned xb_add(unsigned* p, unsigned v) { return __hip_atomic_fetch_add(p, v, __ATOMIC_RELAXED, __HIP_MEMORY_SCOPE_AGENT); }
; __device__ __forceinline__ void xcd_barrier(const XcdBarrier& b, const bool leader) {
;     ...
;             __builtin_amdgcn_fence(__ATOMIC_ACQUIRE, "agent");
;             xb_add(&bar[XB_XGEN(b.x)], 1u);
;             asm volatile("s_waitcnt vmcnt(0)" ::: "memory");
.LBB0_1146:
	s_or_b64 exec, exec, s[10:11]
	s_mov_b64 s[10:11], exec
	v_mbcnt_lo_u32_b32 v0, s10, 0
	v_mbcnt_hi_u32_b32 v0, s11, v0
	v_cmp_eq_u32_e32 vcc, 0, v0
	s_waitcnt vmcnt(0)
	s_and_saveexec_b64 s[12:13], vcc
	s_cbranch_execz .LBB0_1148
	s_bcnt1_i32_b64 s0, s[10:11]
	v_mov_b32_e32 v0, 0x2000
	v_mov_b32_e32 v1, s0
	global_atomic_add v0, v1, s[6:7] offset:1024
.LBB0_1148:
	s_or_b64 exec, exec, s[12:13]
	buffer_inv sc1
	s_waitcnt vmcnt(0)

; __device__ __forceinline__ unsigned xb_add(unsigned* p, unsigned v) { return __hip_atomic_fetch_add(p, v, __ATOMIC_RELAXED, __HIP_MEMORY_SCOPE_AGENT); }
; __device__ __forceinline__ void xcd_barrier(const XcdBarrier& b, const bool leader) {
;     ...
;             __builtin_amdgcn_fence(__ATOMIC_ACQUIRE, "agent");
;             xb_add(&bar[XB_XGEN(b.x)], 1u);
;             asm volatile("s_waitcnt vmcnt(0)" ::: "memory");
.LBB0_1229:
	s_or_b64 exec, exec, s[4:5]
	s_mov_b64 s[4:5], exec
	v_mbcnt_lo_u32_b32 v0, s4, 0
	v_mbcnt_hi_u32_b32 v0, s5, v0
	v_cmp_eq_u32_e32 vcc, 0, v0
	s_waitcnt vmcnt(0)
	s_and_saveexec_b64 s[8:9], vcc
	s_cbranch_execz .LBB0_1231
	s_bcnt1_i32_b64 s0, s[4:5]
	v_mov_b32_e32 v0, 0x2000
	v_mov_b32_e32 v1, s0
	global_atomic_add v0, v1, s[6:7] offset:1024
.LBB0_1231:
	s_or_b64 exec, exec, s[8:9]
	buffer_inv sc1
	s_waitcnt vmcnt(0)
